# phase-0 modulation GEMV: redundant clamped items skipped on the virtual blocks beyond the 288 real items
# baseline (speedup 1.0000x reference)
; DI void mod_item(const Params& p, int item, char* smem) {
;     ...
;         for (int i = 0; i < 36; ++i) { const int idx = tid + THREADS * i, rr = idx >> 10, k = idx & 1023; cv[i] = rr < 8 ? p.c[rr * 1024 + k] : p.c_ctx[k]; }
.LBB0_611:
	v_readlane_b32 s0, v253, 4
	s_mul_i32 s0, s13, s0
	s_add_i32 s0, s0, s16
	s_cmpk_gt_i32 s0, 0x11f
	s_cbranch_scc1 .LBB0_616
	v_mov_b32_e32 v40, v228
	s_movk_i32 s0, 0x1f00
	v_and_b32_e32 v2, 0x3ff, v40
	v_add_u32_e32 v8, 0x100, v40
	s_waitcnt vmcnt(25)
	v_ashrrev_i32_e32 v41, 31, v40
	v_lshlrev_b32_e32 v160, 2, v2
	v_and_b32_e32 v8, 0x3ff, v8
	v_lshl_add_u64 v[0:1], v[40:41], 2, s[78:79]
	v_lshl_add_u64 v[2:3], s[82:83], 0, v[160:161]
	v_cmp_gt_i32_e32 vcc, s18, v40
	v_lshlrev_b32_e32 v160, 2, v8
	v_add_u32_e32 v10, 0x200, v40
	v_cndmask_b32_e32 v5, v3, v1, vcc
	v_cndmask_b32_e32 v4, v2, v0, vcc
	v_lshl_add_u64 v[6:7], v[0:1], 0, s[52:53]
	v_lshl_add_u64 v[8:9], s[82:83], 0, v[160:161]
	v_cmp_gt_i32_e32 vcc, s0, v40
	s_mov_b64 s[0:1], 0x800
	v_and_b32_e32 v10, 0x3ff, v10
	v_cndmask_b32_e32 v7, v9, v7, vcc
	v_cndmask_b32_e32 v6, v8, v6, vcc
	v_lshl_add_u64 v[8:9], v[0:1], 0, s[0:1]
	v_lshlrev_b32_e32 v160, 2, v10
	s_movk_i32 s0, 0x1e00
	v_add_u32_e32 v12, 0x300, v40
	v_lshl_add_u64 v[10:11], s[82:83], 0, v[160:161]
	v_cmp_gt_i32_e32 vcc, s0, v40
	s_mov_b64 s[0:1], 0xc00
	v_and_b32_e32 v12, 0x3ff, v12
	v_cndmask_b32_e32 v9, v11, v9, vcc
	v_cndmask_b32_e32 v8, v10, v8, vcc
	v_lshl_add_u64 v[10:11], v[0:1], 0, s[0:1]
	v_lshlrev_b32_e32 v160, 2, v12
	s_movk_i32 s0, 0x1d00
	v_lshl_add_u64 v[12:13], s[82:83], 0, v[160:161]
	v_cmp_gt_i32_e32 vcc, s0, v40
	s_movk_i32 s0, 0x1c00
	v_add_u32_e32 v16, 0x500, v40
	v_cndmask_b32_e32 v13, v13, v11, vcc
	v_cndmask_b32_e32 v12, v12, v10, vcc
	v_cmp_gt_i32_e32 vcc, s0, v40
	s_mov_b64 s[0:1], 0x1400
	v_and_b32_e32 v16, 0x3ff, v16
	v_lshl_add_u64 v[10:11], v[0:1], 0, s[34:35]
	v_lshl_add_u64 v[14:15], v[0:1], 0, s[0:1]
	v_lshlrev_b32_e32 v160, 2, v16
	s_movk_i32 s0, 0x1b00
	v_add_u32_e32 v18, 0x600, v40
	v_cndmask_b32_e32 v11, v3, v11, vcc
	v_cndmask_b32_e32 v10, v2, v10, vcc
	v_lshl_add_u64 v[16:17], s[82:83], 0, v[160:161]
	v_cmp_gt_i32_e32 vcc, s0, v40
	s_mov_b64 s[0:1], 0x1800
	v_and_b32_e32 v18, 0x3ff, v18
	v_cndmask_b32_e32 v15, v17, v15, vcc
	v_cndmask_b32_e32 v14, v16, v14, vcc
	v_lshl_add_u64 v[16:17], v[0:1], 0, s[0:1]
	v_lshlrev_b32_e32 v160, 2, v18
	s_movk_i32 s0, 0x1a00
	v_add_u32_e32 v20, 0x700, v40
	v_lshl_add_u64 v[18:19], s[82:83], 0, v[160:161]
	v_cmp_gt_i32_e32 vcc, s0, v40
	s_mov_b64 s[0:1], 0x1c00
	v_and_b32_e32 v20, 0x3ff, v20
	v_cndmask_b32_e32 v17, v19, v17, vcc
	v_cndmask_b32_e32 v16, v18, v16, vcc
	v_lshl_add_u64 v[18:19], v[0:1], 0, s[0:1]
	v_lshlrev_b32_e32 v160, 2, v20
	s_movk_i32 s0, 0x1900
	s_waitcnt vmcnt(17)
	v_lshl_add_u64 v[20:21], s[82:83], 0, v[160:161]
	v_cmp_gt_i32_e32 vcc, s0, v40
	s_mov_b64 s[0:1], 0x2000
	v_add_u32_e32 v24, 0x900, v40
	v_cndmask_b32_e32 v19, v21, v19, vcc
	v_cndmask_b32_e32 v18, v20, v18, vcc
	v_lshl_add_u64 v[20:21], v[0:1], 0, s[0:1]
	s_movk_i32 s0, 0x1800
	v_cmp_gt_i32_e32 vcc, s0, v40
	s_mov_b64 s[0:1], 0x2400
	v_and_b32_e32 v24, 0x3ff, v24
	v_add_u32_e32 v26, 0xa00, v40
	s_waitcnt vmcnt(16)
	v_lshl_add_u64 v[22:23], v[0:1], 0, s[0:1]
	v_lshlrev_b32_e32 v160, 2, v24
	s_movk_i32 s0, 0x1700
	v_and_b32_e32 v26, 0x3ff, v26
	v_cndmask_b32_e32 v21, v3, v21, vcc
	v_cndmask_b32_e32 v20, v2, v20, vcc
	v_lshl_add_u64 v[24:25], s[82:83], 0, v[160:161]
	v_cmp_gt_i32_e32 vcc, s0, v40
	s_mov_b64 s[0:1], 0x2800
	v_lshlrev_b32_e32 v160, 2, v26
	v_add_u32_e32 v28, 0xb00, v40
	v_cndmask_b32_e32 v23, v25, v23, vcc
	v_cndmask_b32_e32 v22, v24, v22, vcc
	v_lshl_add_u64 v[24:25], v[0:1], 0, s[0:1]
	v_lshl_add_u64 v[26:27], s[82:83], 0, v[160:161]
	v_cmp_gt_i32_e32 vcc, s24, v40
	s_mov_b64 s[0:1], 0x2c00
	v_and_b32_e32 v28, 0x3ff, v28
	v_cndmask_b32_e32 v25, v27, v25, vcc
	v_cndmask_b32_e32 v24, v26, v24, vcc
	v_lshl_add_u64 v[26:27], v[0:1], 0, s[0:1]
	v_lshlrev_b32_e32 v160, 2, v28
	s_movk_i32 s0, 0x1500
	v_lshl_add_u64 v[28:29], s[82:83], 0, v[160:161]
	v_cmp_gt_i32_e32 vcc, s0, v40
	s_mov_b64 s[0:1], 0x3000
	v_add_u32_e32 v32, 0xd00, v40
	v_cndmask_b32_e32 v27, v29, v27, vcc
	v_cndmask_b32_e32 v26, v28, v26, vcc
	v_lshl_add_u64 v[28:29], v[0:1], 0, s[0:1]
	s_movk_i32 s0, 0x1400
	v_cmp_gt_i32_e32 vcc, s0, v40
	s_mov_b64 s[0:1], 0x3400
	v_and_b32_e32 v32, 0x3ff, v32
	v_lshl_add_u64 v[30:31], v[0:1], 0, s[0:1]
	v_lshlrev_b32_e32 v160, 2, v32
	s_movk_i32 s0, 0x1300
	v_add_u32_e32 v34, 0xe00, v40
	v_cndmask_b32_e32 v29, v3, v29, vcc
	v_cndmask_b32_e32 v28, v2, v28, vcc
	v_lshl_add_u64 v[32:33], s[82:83], 0, v[160:161]
	v_cmp_gt_i32_e32 vcc, s0, v40
	s_mov_b64 s[0:1], 0x3800
	v_and_b32_e32 v34, 0x3ff, v34
	v_cndmask_b32_e32 v31, v33, v31, vcc
	v_cndmask_b32_e32 v30, v32, v30, vcc
	v_lshl_add_u64 v[32:33], v[0:1], 0, s[0:1]
	v_lshlrev_b32_e32 v160, 2, v34
	s_movk_i32 s0, 0x1200
	v_add_u32_e32 v36, 0xf00, v40
	v_lshl_add_u64 v[34:35], s[82:83], 0, v[160:161]
	v_cmp_gt_i32_e32 vcc, s0, v40
	s_mov_b64 s[0:1], 0x3c00
	v_and_b32_e32 v36, 0x3ff, v36
	v_cndmask_b32_e32 v33, v35, v33, vcc
	v_cndmask_b32_e32 v32, v34, v32, vcc
	v_lshl_add_u64 v[34:35], v[0:1], 0, s[0:1]
	v_lshlrev_b32_e32 v160, 2, v36
	s_movk_i32 s0, 0x1100
	v_add_u32_e32 v41, 0x1100, v40
	v_lshl_add_u64 v[36:37], s[82:83], 0, v[160:161]
	v_cmp_gt_i32_e32 vcc, s0, v40
	s_mov_b64 s[0:1], 0x4000
	v_and_b32_e32 v41, 0x3ff, v41
	v_cndmask_b32_e32 v35, v37, v35, vcc
	v_cndmask_b32_e32 v34, v36, v34, vcc
	v_lshl_add_u64 v[36:37], v[0:1], 0, s[0:1]
	s_mov_b64 s[0:1], 0x4400
	v_lshlrev_b32_e32 v160, 2, v41
	v_add_u32_e32 v41, 0x1200, v40
	v_cmp_gt_i32_e32 vcc, s54, v40
	v_lshl_add_u64 v[38:39], v[0:1], 0, s[0:1]
	s_movk_i32 s0, 0xf00
	v_and_b32_e32 v41, 0x3ff, v41
	v_cndmask_b32_e32 v37, v3, v37, vcc
	v_cndmask_b32_e32 v36, v2, v36, vcc
	v_lshl_add_u64 v[42:43], s[82:83], 0, v[160:161]
	v_cmp_gt_i32_e32 vcc, s0, v40
; DI void mod_item(const Params& p, int item, char* smem) {
;     ...
;         for (int i = 0; i < 36; ++i) { const int idx = tid + THREADS * i, rr = idx >> 10, k = idx & 1023; cv[i] = rr < 8 ? p.c[rr * 1024 + k] : p.c_ctx[k]; }
	s_mov_b64 s[0:1], 0x4800
	v_lshlrev_b32_e32 v160, 2, v41
	v_add_u32_e32 v41, 0x1300, v40
	v_cndmask_b32_e32 v39, v43, v39, vcc
	v_cndmask_b32_e32 v38, v42, v38, vcc
	v_lshl_add_u64 v[42:43], v[0:1], 0, s[0:1]
	s_movk_i32 s0, 0xe00
	v_and_b32_e32 v41, 0x3ff, v41
	v_lshl_add_u64 v[44:45], s[82:83], 0, v[160:161]
	v_cmp_gt_i32_e32 vcc, s0, v40
	s_mov_b64 s[0:1], 0x4c00
	v_lshlrev_b32_e32 v160, 2, v41
	v_add_u32_e32 v41, 0x1500, v40
	v_cndmask_b32_e32 v45, v45, v43, vcc
	v_cndmask_b32_e32 v44, v44, v42, vcc
	v_lshl_add_u64 v[42:43], v[0:1], 0, s[0:1]
	s_movk_i32 s0, 0xd00
	v_and_b32_e32 v41, 0x3ff, v41
	v_lshl_add_u64 v[46:47], s[82:83], 0, v[160:161]
	v_cmp_gt_i32_e32 vcc, s0, v40
	s_mov_b64 s[0:1], 0x5000
	v_lshlrev_b32_e32 v160, 2, v41
	v_add_u32_e32 v41, 0x1600, v40
	v_cndmask_b32_e32 v47, v47, v43, vcc
	v_cndmask_b32_e32 v46, v46, v42, vcc
	v_lshl_add_u64 v[42:43], v[0:1], 0, s[0:1]
	s_movk_i32 s0, 0xc00
	v_and_b32_e32 v41, 0x3ff, v41
	v_cmp_gt_i32_e32 vcc, s0, v40
	s_mov_b64 s[0:1], 0x5400
	v_lshl_add_u64 v[50:51], s[82:83], 0, v[160:161]
	v_lshlrev_b32_e32 v160, 2, v41
	v_add_u32_e32 v41, 0x1700, v40
	v_cndmask_b32_e32 v49, v3, v43, vcc
	v_cndmask_b32_e32 v48, v2, v42, vcc
	v_lshl_add_u64 v[42:43], v[0:1], 0, s[0:1]
	v_cmp_gt_i32_e32 vcc, s94, v40
	s_mov_b64 s[0:1], 0x5800
	v_and_b32_e32 v41, 0x3ff, v41
	v_cndmask_b32_e32 v51, v51, v43, vcc
	v_cndmask_b32_e32 v50, v50, v42, vcc
	v_lshl_add_u64 v[42:43], v[0:1], 0, s[0:1]
	v_lshl_add_u64 v[52:53], s[82:83], 0, v[160:161]
	v_cmp_gt_i32_e32 vcc, s19, v40
	s_mov_b64 s[0:1], 0x5c00
	v_lshlrev_b32_e32 v160, 2, v41
	v_cndmask_b32_e32 v53, v53, v43, vcc
	v_cndmask_b32_e32 v52, v52, v42, vcc
	v_lshl_add_u64 v[42:43], v[0:1], 0, s[0:1]
	v_lshl_add_u64 v[54:55], s[82:83], 0, v[160:161]
	v_cmp_gt_i32_e32 vcc, s95, v40
	s_mov_b64 s[0:1], 0x6000
	v_add_u32_e32 v41, 0x1900, v40
	v_cndmask_b32_e32 v55, v55, v43, vcc
	v_cndmask_b32_e32 v54, v54, v42, vcc
	v_lshl_add_u64 v[42:43], v[0:1], 0, s[0:1]
	s_movk_i32 s0, 0x800
	v_cmp_gt_i32_e32 vcc, s0, v40
	s_mov_b64 s[0:1], 0x6400
	v_and_b32_e32 v41, 0x3ff, v41
	v_cndmask_b32_e32 v57, v3, v43, vcc
	v_cndmask_b32_e32 v56, v2, v42, vcc
	v_lshl_add_u64 v[42:43], v[0:1], 0, s[0:1]
	v_lshlrev_b32_e32 v160, 2, v41
	s_movk_i32 s0, 0x700
	v_add_u32_e32 v41, 0x1a00, v40
	v_lshl_add_u64 v[58:59], s[82:83], 0, v[160:161]
	v_cmp_gt_i32_e32 vcc, s0, v40
	s_mov_b64 s[0:1], 0x6800
	v_and_b32_e32 v41, 0x3ff, v41
	v_cndmask_b32_e32 v59, v59, v43, vcc
	v_cndmask_b32_e32 v58, v58, v42, vcc
	v_lshl_add_u64 v[42:43], v[0:1], 0, s[0:1]
	v_lshlrev_b32_e32 v160, 2, v41
	s_movk_i32 s0, 0x600
	v_add_u32_e32 v41, 0x1b00, v40
	v_lshl_add_u64 v[60:61], s[82:83], 0, v[160:161]
	v_cmp_gt_i32_e32 vcc, s0, v40
	s_mov_b64 s[0:1], 0x6c00
	v_and_b32_e32 v41, 0x3ff, v41
	v_cndmask_b32_e32 v61, v61, v43, vcc
	v_cndmask_b32_e32 v60, v60, v42, vcc
	v_lshl_add_u64 v[42:43], v[0:1], 0, s[0:1]
	v_lshlrev_b32_e32 v160, 2, v41
	s_movk_i32 s0, 0x500
	v_lshl_add_u64 v[62:63], s[82:83], 0, v[160:161]
	v_cmp_gt_i32_e32 vcc, s0, v40
	s_mov_b64 s[0:1], 0x7000
	v_add_u32_e32 v41, 0x1d00, v40
	v_cndmask_b32_e32 v63, v63, v43, vcc
	v_cndmask_b32_e32 v62, v62, v42, vcc
	v_lshl_add_u64 v[42:43], v[0:1], 0, s[0:1]
	s_movk_i32 s0, 0x400
	v_and_b32_e32 v41, 0x3ff, v41
	v_cmp_gt_i32_e32 vcc, s0, v40
	s_mov_b64 s[0:1], 0x7400
	v_lshlrev_b32_e32 v160, 2, v41
	v_add_u32_e32 v41, 0x1e00, v40
	v_cndmask_b32_e32 v65, v3, v43, vcc
	v_cndmask_b32_e32 v64, v2, v42, vcc
	v_lshl_add_u64 v[42:43], v[0:1], 0, s[0:1]
	s_movk_i32 s0, 0x300
	v_and_b32_e32 v41, 0x3ff, v41
	v_lshl_add_u64 v[66:67], s[82:83], 0, v[160:161]
	v_cmp_gt_i32_e32 vcc, s0, v40
	s_mov_b64 s[0:1], 0x7800
	v_lshlrev_b32_e32 v160, 2, v41
	v_add_u32_e32 v41, 0x1f00, v40
	v_cndmask_b32_e32 v67, v67, v43, vcc
	v_cndmask_b32_e32 v66, v66, v42, vcc
	v_lshl_add_u64 v[42:43], v[0:1], 0, s[0:1]
	s_movk_i32 s0, 0x200
	v_and_b32_e32 v41, 0x3ff, v41
	v_lshl_add_u64 v[68:69], s[82:83], 0, v[160:161]
	v_cmp_gt_i32_e32 vcc, s0, v40
	s_mov_b64 s[0:1], 0x7c00
	v_lshlrev_b32_e32 v160, 2, v41
	v_cndmask_b32_e32 v69, v69, v43, vcc
	v_cndmask_b32_e32 v68, v68, v42, vcc
	v_lshl_add_u64 v[42:43], v[0:1], 0, s[0:1]
	v_lshl_add_u64 v[70:71], s[82:83], 0, v[160:161]
	v_cmp_gt_i32_e32 vcc, s17, v40
	global_load_dword v72, v[6:7], off
	global_load_dword v73, v[8:9], off
	v_cndmask_b32_e32 v71, v71, v43, vcc
	global_load_dword v43, v[4:5], off
	s_mov_b64 s[0:1], 0x8000
	global_load_dword v12, v[12:13], off
	v_add_u32_e32 v41, 0x2100, v40
	global_load_dword v10, v[10:11], off
	v_cndmask_b32_e32 v70, v70, v42, vcc
	global_load_dword v11, v[14:15], off
	v_lshl_add_u64 v[4:5], v[0:1], 0, s[0:1]
	v_cmp_gt_i32_e32 vcc, 0, v40
	s_mov_b64 s[0:1], 0x8400
	v_and_b32_e32 v6, 0x3ff, v41
	v_cndmask_b32_e32 v3, v3, v5, vcc
	v_cndmask_b32_e32 v2, v2, v4, vcc
	v_lshl_add_u64 v[4:5], v[0:1], 0, s[0:1]
	v_lshlrev_b32_e32 v160, 2, v6
	s_movk_i32 s0, 0xff00
	v_add_u32_e32 v8, 0x2200, v40
	v_lshl_add_u64 v[6:7], s[82:83], 0, v[160:161]
	v_cmp_gt_i32_e32 vcc, s0, v40
	s_mov_b64 s[0:1], 0x8800
	v_and_b32_e32 v8, 0x3ff, v8
	v_cndmask_b32_e32 v5, v7, v5, vcc
	v_cndmask_b32_e32 v4, v6, v4, vcc
	v_lshl_add_u64 v[6:7], v[0:1], 0, s[0:1]
	v_lshlrev_b32_e32 v160, 2, v8
	s_movk_i32 s0, 0xfe00
	v_lshl_add_u64 v[8:9], s[82:83], 0, v[160:161]
	v_cmp_gt_i32_e32 vcc, s0, v40
	global_load_dword v13, v[16:17], off
	s_mov_b64 s[0:1], 0x8c00
	v_cndmask_b32_e32 v6, v8, v6, vcc
	v_add_u32_e32 v8, 0x2300, v40
	v_and_b32_e32 v8, 0x3ff, v8
	v_lshl_add_u64 v[0:1], v[0:1], 0, s[0:1]
	v_lshlrev_b32_e32 v160, 2, v8
	s_movk_i32 s0, 0xfd00
	v_cndmask_b32_e32 v7, v9, v7, vcc
	v_lshl_add_u64 v[8:9], s[82:83], 0, v[160:161]
; DI int otid() { int t = threadIdx.x & 255; asm volatile("" : "+v"(t)); return t; }
; DI void mod_item(const Params& p, int item, char* smem) {
;     ...
;     const int l = item / 144, cgp = item % 144, tid = otid();
;     {
;         float cv[36];
; #pragma unroll
;         for (int i = 0; i < 36; ++i) { const int idx = tid + THREADS * i, rr = idx >> 10, k = idx & 1023; cv[i] = rr < 8 ? p.c[rr * 1024 + k] : p.c_ctx[k]; }
; #pragma unroll
;         for (int i = 0; i < 36; ++i) sc[tid + THREADS * i] = cv[i] * __builtin_amdgcn_rcpf(1.f + __expf(-cv[i]));
;     }
;     __syncthreads();
;     const int cx = tid & 63, kg = tid >> 6, col = cgp * 64 + cx;
	global_load_dword v14, v[18:19], off
	v_cmp_gt_i32_e32 vcc, s0, v40
	global_load_dword v15, v[24:25], off
	v_readlane_b32 s0, v253, 4
	v_cndmask_b32_e32 v1, v9, v1, vcc
	global_load_dword v9, v[20:21], off
	v_cndmask_b32_e32 v0, v8, v0, vcc
	global_load_dword v8, v[22:23], off
	global_load_dword v16, v[26:27], off
	global_load_dword v17, v[28:29], off
	global_load_dword v18, v[30:31], off
	global_load_dword v19, v[32:33], off
	global_load_dword v20, v[34:35], off
	global_load_dword v21, v[36:37], off
	global_load_dword v22, v[38:39], off
	global_load_dword v23, v[44:45], off
	global_load_dword v24, v[46:47], off
	global_load_dword v25, v[48:49], off
	global_load_dword v26, v[50:51], off
	global_load_dword v27, v[52:53], off
	global_load_dword v28, v[54:55], off
	global_load_dword v29, v[56:57], off
	global_load_dword v30, v[58:59], off
	global_load_dword v31, v[60:61], off
	global_load_dword v32, v[62:63], off
	global_load_dword v33, v[64:65], off
	global_load_dword v34, v[66:67], off
	global_load_dword v35, v[68:69], off
	global_load_dword v36, v[70:71], off
	s_nop 0
	global_load_dword v2, v[2:3], off
	s_nop 0
	global_load_dword v3, v[4:5], off
	s_nop 0
	global_load_dword v4, v[6:7], off
	s_mul_i32 s0, s13, s0
	global_load_dword v0, v[0:1], off
	s_add_i32 s0, s0, s16
	s_min_i32 s0, s0, 0x11f
	s_mul_hi_i32 s1, s0, 0x38e38e39
	s_lshr_b32 s4, s1, 31
	s_ashr_i32 s1, s1, 5
	s_add_i32 s4, s1, s4
	s_mul_i32 s1, s4, 0x90
	v_ashrrev_i32_e32 v75, 6, v40
	s_sub_i32 s0, s0, s1
	v_and_b32_e32 v41, 63, v40
	v_lshl_or_b32 v42, s0, 6, v41
	v_lshl_add_u32 v77, v75, 10, s25
	s_waitcnt vmcnt(35)
	v_mul_f32_e32 v6, 0xbfb8aa3b, v72
	v_exp_f32_e32 v6, v6
	s_waitcnt vmcnt(34)
	v_mul_f32_e32 v7, 0xbfb8aa3b, v73
	s_waitcnt vmcnt(33)
	v_mul_f32_e32 v37, 0xbfb8aa3b, v43
	v_exp_f32_e32 v37, v37
	v_exp_f32_e32 v7, v7
	v_add_f32_e32 v6, 1.0, v6
	v_rcp_f32_e32 v6, v6
	v_add_f32_e32 v5, 1.0, v37
	s_waitcnt vmcnt(32)
	v_mul_f32_e32 v37, 0xbfb8aa3b, v12
	v_exp_f32_e32 v37, v37
	v_rcp_f32_e32 v5, v5
	v_add_f32_e32 v7, 1.0, v7
	v_rcp_f32_e32 v7, v7
	v_add_f32_e32 v37, 1.0, v37
	v_rcp_f32_e32 v37, v37
	v_mul_f32_e32 v1, v43, v5
	v_lshl_add_u32 v5, v40, 2, s25
	v_mul_f32_e32 v6, v72, v6
	ds_write2st64_b32 v5, v1, v6 offset1:4
	v_mul_f32_e32 v1, v73, v7
	v_mul_f32_e32 v6, v12, v37
	s_waitcnt vmcnt(31)
	v_mul_f32_e32 v7, 0xbfb8aa3b, v10
	s_waitcnt vmcnt(30)
	v_mul_f32_e32 v12, 0xbfb8aa3b, v11
	v_exp_f32_e32 v7, v7
	v_exp_f32_e32 v12, v12
	ds_write2st64_b32 v5, v1, v6 offset0:8 offset1:12
	v_ashrrev_i32_e32 v43, 31, v42
	v_add_f32_e32 v1, 1.0, v7
	v_add_f32_e32 v6, 1.0, v12
	v_rcp_f32_e32 v1, v1
	v_rcp_f32_e32 v6, v6
	s_waitcnt vmcnt(29)
	v_mul_f32_e32 v7, 0xbfb8aa3b, v13
	v_exp_f32_e32 v7, v7
	v_mul_f32_e32 v1, v10, v1
	v_mul_f32_e32 v6, v11, v6
	ds_write2st64_b32 v5, v1, v6 offset0:16 offset1:20
	v_add_f32_e32 v1, 1.0, v7
	v_rcp_f32_e32 v1, v1
	s_waitcnt vmcnt(28)
	v_mul_f32_e32 v6, 0xbfb8aa3b, v14
	v_exp_f32_e32 v6, v6
	v_mul_f32_e32 v1, v13, v1
	s_waitcnt vmcnt(26)
	v_mul_f32_e32 v7, 0xbfb8aa3b, v9
	v_exp_f32_e32 v7, v7
	v_add_f32_e32 v6, 1.0, v6
	v_rcp_f32_e32 v6, v6
	s_waitcnt vmcnt(25)
	v_mul_f32_e32 v10, 0xbfb8aa3b, v8
	v_add_f32_e32 v7, 1.0, v7
	v_rcp_f32_e32 v7, v7
	v_mul_f32_e32 v6, v14, v6
	v_exp_f32_e32 v10, v10
	ds_write2st64_b32 v5, v1, v6 offset0:24 offset1:28
	v_mul_f32_e32 v1, v9, v7
	v_mul_f32_e32 v7, 0xbfb8aa3b, v15
	v_exp_f32_e32 v7, v7
	v_add_f32_e32 v6, 1.0, v10
	s_waitcnt vmcnt(24)
	v_mul_f32_e32 v9, 0xbfb8aa3b, v16
	v_exp_f32_e32 v9, v9
	v_rcp_f32_e32 v6, v6
	v_add_f32_e32 v7, 1.0, v7
	v_rcp_f32_e32 v7, v7
	v_add_f32_e32 v9, 1.0, v9
	v_mul_f32_e32 v6, v8, v6
	v_rcp_f32_e32 v9, v9
	ds_write2st64_b32 v5, v1, v6 offset0:32 offset1:36
	v_mul_f32_e32 v1, v15, v7
	s_waitcnt vmcnt(23)
	v_mul_f32_e32 v7, 0xbfb8aa3b, v17
	s_waitcnt vmcnt(22)
	v_mul_f32_e32 v8, 0xbfb8aa3b, v18
	v_exp_f32_e32 v7, v7
	v_exp_f32_e32 v8, v8
	v_mul_f32_e32 v6, v16, v9
	ds_write2st64_b32 v5, v1, v6 offset0:40 offset1:44
	v_add_f32_e32 v1, 1.0, v7
	v_add_f32_e32 v6, 1.0, v8
	v_rcp_f32_e32 v1, v1
	v_rcp_f32_e32 v6, v6
	s_waitcnt vmcnt(21)
	v_mul_f32_e32 v7, 0xbfb8aa3b, v19
	v_exp_f32_e32 v7, v7
	v_mul_f32_e32 v1, v17, v1
	v_mul_f32_e32 v6, v18, v6
	ds_write2st64_b32 v5, v1, v6 offset0:48 offset1:52
	s_waitcnt vmcnt(20)
; DI void mod_item(const Params& p, int item, char* smem) {
;     ...
;         for (int i = 0; i < 36; ++i) sc[tid + THREADS * i] = cv[i] * __builtin_amdgcn_rcpf(1.f + __expf(-cv[i]));
;     }
;     __syncthreads();
;     const int cx = tid & 63, kg = tid >> 6, col = cgp * 64 + cx;
;     const float* w = p.w_ada + (size_t)l * 1024 * 9216 + col;
;     float acc[9];
; #pragma unroll
;     for (int rr = 0; rr < 9; ++rr) acc[rr] = 0.f;
	v_mul_f32_e32 v6, 0xbfb8aa3b, v20
	v_add_f32_e32 v1, 1.0, v7
	v_exp_f32_e32 v6, v6
	s_waitcnt vmcnt(19)
	v_mul_f32_e32 v7, 0xbfb8aa3b, v21
	v_exp_f32_e32 v7, v7
	v_rcp_f32_e32 v1, v1
	v_add_f32_e32 v6, 1.0, v6
	v_rcp_f32_e32 v6, v6
	v_add_f32_e32 v7, 1.0, v7
	s_waitcnt vmcnt(18)
	v_mul_f32_e32 v8, 0xbfb8aa3b, v22
	v_rcp_f32_e32 v7, v7
	v_exp_f32_e32 v8, v8
	v_mul_f32_e32 v1, v19, v1
	v_mul_f32_e32 v6, v20, v6
	ds_write2st64_b32 v5, v1, v6 offset0:56 offset1:60
	v_mul_f32_e32 v1, v21, v7
	v_add_f32_e32 v6, 1.0, v8
	s_waitcnt vmcnt(17)
	v_mul_f32_e32 v7, 0xbfb8aa3b, v23
	s_waitcnt vmcnt(16)
	v_mul_f32_e32 v8, 0xbfb8aa3b, v24
	v_exp_f32_e32 v7, v7
	v_exp_f32_e32 v8, v8
	v_rcp_f32_e32 v6, v6
	v_add_f32_e32 v7, 1.0, v7
	v_add_f32_e32 v8, 1.0, v8
	v_rcp_f32_e32 v7, v7
	v_rcp_f32_e32 v8, v8
	v_mul_f32_e32 v6, v22, v6
	ds_write2st64_b32 v5, v1, v6 offset0:64 offset1:68
	v_mul_f32_e32 v1, v23, v7
	v_mul_f32_e32 v6, v24, v8
	s_waitcnt vmcnt(15)
	v_mul_f32_e32 v7, 0xbfb8aa3b, v25
	s_waitcnt vmcnt(14)
	v_mul_f32_e32 v8, 0xbfb8aa3b, v26
	v_exp_f32_e32 v7, v7
	v_exp_f32_e32 v8, v8
	ds_write2st64_b32 v5, v1, v6 offset0:72 offset1:76
	v_add_f32_e32 v1, 1.0, v7
	v_add_f32_e32 v6, 1.0, v8
	v_rcp_f32_e32 v1, v1
	v_rcp_f32_e32 v6, v6
	s_waitcnt vmcnt(13)
	v_mul_f32_e32 v7, 0xbfb8aa3b, v27
	v_exp_f32_e32 v7, v7
	v_mul_f32_e32 v1, v25, v1
	v_mul_f32_e32 v6, v26, v6
	ds_write2st64_b32 v5, v1, v6 offset0:80 offset1:84
	s_waitcnt vmcnt(12)
	v_mul_f32_e32 v6, 0xbfb8aa3b, v28
	v_add_f32_e32 v1, 1.0, v7
	v_exp_f32_e32 v6, v6
	s_waitcnt vmcnt(11)
	v_mul_f32_e32 v7, 0xbfb8aa3b, v29
	v_exp_f32_e32 v7, v7
	v_rcp_f32_e32 v1, v1
	v_add_f32_e32 v6, 1.0, v6
	v_rcp_f32_e32 v6, v6
	v_add_f32_e32 v7, 1.0, v7
	s_waitcnt vmcnt(10)
	v_mul_f32_e32 v8, 0xbfb8aa3b, v30
	v_rcp_f32_e32 v7, v7
	v_exp_f32_e32 v8, v8
	v_mul_f32_e32 v1, v27, v1
	v_mul_f32_e32 v6, v28, v6
	ds_write2st64_b32 v5, v1, v6 offset0:88 offset1:92
	v_mul_f32_e32 v1, v29, v7
	v_add_f32_e32 v6, 1.0, v8
	s_waitcnt vmcnt(9)
	v_mul_f32_e32 v7, 0xbfb8aa3b, v31
	s_waitcnt vmcnt(8)
	v_mul_f32_e32 v8, 0xbfb8aa3b, v32
	v_exp_f32_e32 v7, v7
	v_exp_f32_e32 v8, v8
	v_rcp_f32_e32 v6, v6
	v_add_f32_e32 v7, 1.0, v7
	v_add_f32_e32 v8, 1.0, v8
	v_rcp_f32_e32 v7, v7
	v_rcp_f32_e32 v8, v8
	v_mul_f32_e32 v6, v30, v6
	ds_write2st64_b32 v5, v1, v6 offset0:96 offset1:100
	v_mul_f32_e32 v1, v31, v7
	v_mul_f32_e32 v6, v32, v8
	s_waitcnt vmcnt(7)
	v_mul_f32_e32 v7, 0xbfb8aa3b, v33
	s_waitcnt vmcnt(6)
	v_mul_f32_e32 v8, 0xbfb8aa3b, v34
	v_exp_f32_e32 v7, v7
	v_exp_f32_e32 v8, v8
	ds_write2st64_b32 v5, v1, v6 offset0:104 offset1:108
	v_add_f32_e32 v1, 1.0, v7
	v_add_f32_e32 v6, 1.0, v8
	v_rcp_f32_e32 v1, v1
	v_rcp_f32_e32 v6, v6
	s_waitcnt vmcnt(5)
	v_mul_f32_e32 v7, 0xbfb8aa3b, v35
	v_exp_f32_e32 v7, v7
	v_mul_f32_e32 v1, v33, v1
	v_mul_f32_e32 v6, v34, v6
	ds_write2st64_b32 v5, v1, v6 offset0:112 offset1:116
	s_waitcnt vmcnt(4)
	v_mul_f32_e32 v6, 0xbfb8aa3b, v36
	v_add_f32_e32 v1, 1.0, v7
	v_exp_f32_e32 v6, v6
	s_waitcnt vmcnt(3)
	v_mul_f32_e32 v7, 0xbfb8aa3b, v2
	v_exp_f32_e32 v7, v7
	v_rcp_f32_e32 v1, v1
	v_add_f32_e32 v6, 1.0, v6
	v_rcp_f32_e32 v6, v6
	v_add_f32_e32 v7, 1.0, v7
	v_rcp_f32_e32 v7, v7
	v_mul_f32_e32 v1, v35, v1
	s_waitcnt vmcnt(2)
	v_mul_f32_e32 v8, 0xbfb8aa3b, v3
	v_mul_f32_e32 v6, v36, v6
	v_exp_f32_e32 v8, v8
	ds_write2st64_b32 v5, v1, v6 offset0:120 offset1:124
	v_mul_f32_e32 v1, v2, v7
	s_waitcnt vmcnt(1)
	v_mul_f32_e32 v6, 0xbfb8aa3b, v4
	s_waitcnt vmcnt(0)
	v_mul_f32_e32 v7, 0xbfb8aa3b, v0
	v_exp_f32_e32 v6, v6
	v_exp_f32_e32 v7, v7
	v_add_f32_e32 v2, 1.0, v8
	v_rcp_f32_e32 v2, v2
	v_add_f32_e32 v6, 1.0, v6
	v_add_f32_e32 v7, 1.0, v7
	v_rcp_f32_e32 v6, v6
	v_rcp_f32_e32 v7, v7
	v_mul_f32_e32 v2, v3, v2
	ds_write2st64_b32 v5, v1, v2 offset0:128 offset1:132
	v_mul_f32_e32 v1, v4, v6
	v_mul_f32_e32 v0, v0, v7
	ds_write2st64_b32 v5, v1, v0 offset0:136 offset1:140
	v_lshlrev_b32_e32 v0, 8, v75
	v_mad_i64_i32 v[0:1], s[0:1], v0, s96, 0
	v_mad_i64_i32 v[0:1], s[0:1], s4, v238, v[0:1]
	v_lshl_add_u64 v[0:1], v[42:43], 2, v[0:1]
	v_mov_b32_e32 v36, 0
	v_lshl_add_u64 v[44:45], s[84:85], 0, v[0:1]
	v_mov_b32_e32 v37, v36
	v_mov_b32_e32 v38, v36
	v_mov_b32_e32 v39, v36
	v_mov_b32_e32 v32, v36
	v_mov_b32_e32 v33, v36
	v_mov_b32_e32 v70, v36
	v_mov_b32_e32 v71, v36
	v_mov_b32_e32 v79, v36
	s_mov_b64 s[0:1], 0
	s_waitcnt lgkmcnt(0)
	s_barrier
